# MLA attention loop restructured (PV(i-1)+QK(i) | barrier | softmax(i)+staging | barrier, 3 LDS slots, waves 4-7 one barrier behind), original PV fragment read order
# speedup vs baseline: 1.1216x; 1.1216x over previous
; DI int hw_lane() { int l; asm volatile("v_mbcnt_lo_u32_b32 %0, -1, 0\n\tv_mbcnt_hi_u32_b32 %0, -1, %0" : "=v"(l)); return l; }
; #define PH_TID() const int tid = wave0 * 64 + hw_lane(), lane = tid & 63, wave = wave0
; __global__ void __launch_bounds__(512, 2) trunk_fwd(Args a_) {
;     ...
;     for (int ph = ph_lo; ph < ph_hi; ++ph) {
;         const int spx = ph == 0 ? 9 : (ph - 1) % NSP;
;         for (int rep = 0; rep < (((DUPM >> spx) & 1u) ? 2 : 1); ++rep) {
;         if (rep > 0 && coop) xcd_barrier(bar, wave0 * 64 + hw_lane());
;         AP a = (AP)__builtin_amdgcn_kernarg_segment_ptr(); asm volatile("" : "+s"(a));
;     ...
;         int G = gridDim.x, bx = blockIdx.x; asm volatile("" : "+s"(G), "+s"(bx));
;         const int vcu = (G % 8 == 0) ? (bx % 8) * (G / 8) + bx / 8 : bx;
;         unsigned char* ws = a->ws;
;         if (ph == 0) {
;             if (PHM & 512u) { PH_TID(); prologue(a, lds, tid, lane, wave, vcu, G); }
;         } else {
;             const int l = (ph - 1) / NSP, sp = (ph - 1) % NSP;
;             unsigned char* wl = ws + WS_W + (size_t)l * W_LAYER;
.LBB0_15:
	v_writelane_b32 v253, s3, 2
	s_cmp_ge_i32 s48, s49
	s_cbranch_scc1 .LBB0_977
	s_lshr_b32 s33, s10, 6
	s_mul_i32 s4, s33, 0x1200
	s_add_i32 s4, s4, 0
	s_add_i32 s4, s4, 0x10000
	s_lshl_b32 s3, s33, 5
	v_writelane_b32 v253, s4, 3
	s_lshl_b32 s4, s33, 14
	s_add_i32 s7, s4, 0
	s_lshr_b32 s4, s10, 8
	s_and_b32 s5, s3, 0x60
	s_mov_b32 s73, 0
	v_writelane_b32 v253, s5, 4
	s_mul_i32 s5, s4, 0x8400
	s_mul_i32 s72, s4, 0xc0
	s_and_b32 s82, s10, 0xffffffc0
	s_add_i32 s94, s5, 0
	s_lshl_b64 s[8:9], s[72:73], 9
	s_and_b32 s5, s10, 0xffffff00
	v_writelane_b32 v253, s8, 5
	s_cmpk_gt_u32 s10, 0xff
	s_mul_i32 s6, s33, 0xffffc010
	v_writelane_b32 v253, s9, 6
	s_cselect_b64 s[76:77], -1, 0
	s_add_i32 s6, s7, s6
	v_writelane_b32 v253, s7, 7
	s_cmp_eq_u32 s33, 7
	v_writelane_b32 v253, s6, 8
	s_cselect_b64 s[6:7], -1, 0
	v_writelane_b32 v253, s6, 9
	v_lshrrev_b32_e32 v2, 20, v0
	v_lshrrev_b32_e32 v0, 10, v0
	v_writelane_b32 v253, s7, 10
	s_add_u32 s6, s66, 0x200
	s_addc_u32 s7, s67, 0
	v_writelane_b32 v253, s6, 11
	v_or_b32_e32 v0, v0, v2
	s_movk_i32 s37, 0x3ff
	v_writelane_b32 v253, s7, 12
	s_add_u32 s6, s66, 0x1000
	s_addc_u32 s7, s67, 0
	v_writelane_b32 v253, s6, 13
	v_and_or_b32 v0, v0, s37, v1
	v_mbcnt_lo_u32_b32 v1, -1, 0
	v_writelane_b32 v253, s7, 14
	s_add_u32 s6, s66, 0x1100
	s_addc_u32 s7, s67, 0
	v_writelane_b32 v253, s6, 15
	v_mov_b32_e32 v65, 0
	v_mov_b32_e32 v175, 0xc0135761
	v_writelane_b32 v253, s7, 16
	s_add_u32 s6, s66, 0x1200
	s_addc_u32 s7, s67, 0
	v_writelane_b32 v253, s6, 17
	v_mbcnt_hi_u32_b32 v226, -1, v1
	v_mov_b32_e32 v227, 0x1c800000
	v_writelane_b32 v253, s7, 18
	s_add_u32 s6, s66, 0x1300
	s_addc_u32 s7, s67, 0
	v_writelane_b32 v253, s6, 19
	s_cmp_eq_u32 s2, 15
	v_mov_b32_e32 v228, 1
	v_writelane_b32 v253, s7, 20
	s_cselect_b64 s[6:7], -1, 0
	v_writelane_b32 v253, s6, 21
	s_cmp_eq_u32 s2, 14
	v_mov_b32_e32 v229, 0x260
	v_writelane_b32 v253, s7, 22
	s_cselect_b64 s[6:7], -1, 0
	v_writelane_b32 v253, s6, 23
	s_cmp_eq_u32 s2, 13
	v_mov_b32_e32 v230, 0x3c0881c4
	v_writelane_b32 v253, s7, 24
	s_cselect_b64 s[6:7], -1, 0
	v_writelane_b32 v253, s6, 25
	s_cmp_eq_u32 s2, 12
	v_mov_b32_e32 v231, 0xbab64f3b
	v_writelane_b32 v253, s7, 26
	s_cselect_b64 s[6:7], -1, 0
	v_writelane_b32 v253, s6, 27
	s_cmp_eq_u32 s2, 11
	v_mov_b32_e32 v234, 0xf149f2ca
	v_writelane_b32 v253, s7, 28
	s_cselect_b64 s[6:7], -1, 0
	v_writelane_b32 v253, s6, 29
	s_cmp_eq_u32 s2, 10
	v_mov_b32_e32 v252, 0x3e38aa3b
	v_writelane_b32 v253, s7, 30
	s_cselect_b64 s[6:7], -1, 0
	v_writelane_b32 v253, s6, 31
	s_cmp_eq_u32 s2, 9
	v_writelane_b32 v253, s7, 32
	s_cselect_b64 s[6:7], -1, 0
	v_writelane_b32 v253, s6, 33
	s_cmp_eq_u32 s2, 8
	v_writelane_b32 v253, s7, 34
	s_cselect_b64 s[6:7], -1, 0
	v_writelane_b32 v253, s6, 35
	s_cmp_eq_u32 s2, 7
	v_not_b32_e32 v235, 63
	v_writelane_b32 v253, s7, 36
	s_cselect_b64 s[6:7], -1, 0
	v_writelane_b32 v253, s6, 37
	s_cmp_eq_u32 s2, 6
	v_not_b32_e32 v240, 31
	v_writelane_b32 v253, s7, 38
	s_cselect_b64 s[6:7], -1, 0
	v_writelane_b32 v253, s6, 39
	s_cmp_eq_u32 s2, 5
	v_mov_b32_e32 v241, 0x7fc00000
	v_writelane_b32 v253, s7, 40
	s_cselect_b64 s[6:7], -1, 0
	v_writelane_b32 v253, s6, 41
	s_cmp_eq_u32 s2, 4
	s_movk_i32 s83, 0x80
	v_writelane_b32 v253, s7, 42
	s_cselect_b64 s[6:7], -1, 0
	v_writelane_b32 v253, s6, 43
	s_cmp_eq_u32 s2, 3
	s_mov_b32 s50, 0x18000
	v_writelane_b32 v253, s7, 44
	s_cselect_b64 s[6:7], -1, 0
	v_writelane_b32 v253, s6, 45
	s_cmp_eq_u32 s2, 2
	s_mov_b32 s78, 0x2aaaaaab
	v_writelane_b32 v253, s7, 46
	s_cselect_b64 s[6:7], -1, 0
	v_writelane_b32 v253, s6, 47
	s_cmp_eq_u32 s2, 1
	s_mov_b32 s70, 0x2e8ba2e9
	v_writelane_b32 v253, s7, 48
	s_cselect_b64 s[6:7], -1, 0
	v_writelane_b32 v253, s6, 49
	s_cmp_eq_u32 s2, 0
	s_movk_i32 s71, 0x5800
	v_writelane_b32 v253, s7, 50
	s_cselect_b64 s[6:7], -1, 0
	s_lshl_b32 s2, s2, 8
	v_writelane_b32 v253, s6, 51
	s_add_u32 s2, s66, s2
	s_movk_i32 s51, 0x1600
	v_writelane_b32 v253, s7, 52
	s_addc_u32 s6, s67, 0
	s_add_u32 s8, s2, 0x1400
	s_addc_u32 s9, s6, 0
	v_writelane_b32 v253, s8, 53
	s_movk_i32 s53, 0x200
	s_movk_i32 s86, 0x300
	v_writelane_b32 v253, s9, 54
	s_add_u32 s8, s2, 0x2400
	s_addc_u32 s9, s6, 0
	v_writelane_b32 v253, s8, 55
	s_add_u32 s6, s66, 0x3400
	s_addc_u32 s7, s67, 0
	v_writelane_b32 v253, s9, 56
	v_writelane_b32 v253, s6, 57
	s_mov_b32 s87, 0xf800000
	s_movk_i32 s60, 0x5ff
	v_writelane_b32 v253, s7, 58
	s_add_u32 s6, s66, 0x3500
	s_addc_u32 s7, s67, 0
	s_lshl_b32 s2, s79, 8
	s_and_b32 s2, s2, 0x700
	v_writelane_b32 v253, s6, 59
	s_add_u32 s2, s14, s2
	s_movk_i32 s88, 0x7f
	v_writelane_b32 v253, s7, 60
	s_addc_u32 s6, s15, 0
	s_add_u32 s54, s2, 0x1c884000
	s_addc_u32 s55, s6, 0
	s_add_u32 s56, s14, 0x1c803e00
	s_addc_u32 s57, s15, 0
	s_add_u32 s6, s14, 0x1c803e40
	s_addc_u32 s7, s15, 0
	v_writelane_b32 v253, s6, 61
	s_mul_i32 s2, s59, s58
	s_mov_b32 s89, 0x5040100
	v_writelane_b32 v253, s7, 62
	s_add_u32 s6, s14, 0x1c803e20
	s_addc_u32 s7, s15, 0
	v_writelane_b32 v253, s6, 63
	s_mov_b32 s46, 0xdb629599
	s_mov_b32 s47, 0xf534ddc0
	v_writelane_b32 v254, s7, 0
	s_add_u32 s6, s14, 0x1c803e04
	s_addc_u32 s7, s15, 0
	v_writelane_b32 v254, s6, 1
	s_mov_b32 s52, 0xfc2757d1
	s_mov_b64 s[92:93], 0x80
	v_writelane_b32 v254, s7, 2
	s_add_u32 s6, s14, 0x1c803e24
	s_addc_u32 s7, s15, 0
	v_writelane_b32 v254, s6, 3
	s_mov_b64 s[96:97], 0x100
	s_mov_b64 s[80:81], 0xc000
	v_writelane_b32 v254, s7, 4
	s_add_u32 s6, s14, 0x1c803e08
	s_addc_u32 s7, s15, 0
	v_writelane_b32 v254, s6, 5
	s_nop 1
	v_writelane_b32 v254, s7, 6
	s_add_u32 s6, s14, 0x1c803e28
	s_addc_u32 s7, s15, 0
	v_writelane_b32 v254, s6, 7
	s_nop 1
	v_writelane_b32 v254, s7, 8
	s_add_u32 s6, s14, 0x1c803e0c
	s_addc_u32 s7, s15, 0
	v_writelane_b32 v254, s6, 9
	s_nop 1
	v_writelane_b32 v254, s7, 10
	s_add_u32 s6, s14, 0x1c803e2c
	s_addc_u32 s7, s15, 0
	v_writelane_b32 v254, s6, 11
	s_nop 1
	v_writelane_b32 v254, s7, 12
	s_add_u32 s6, s14, 0x1c803e10
	s_addc_u32 s7, s15, 0
	v_writelane_b32 v254, s6, 13
	s_nop 1
	v_writelane_b32 v254, s7, 14
	s_add_u32 s6, s14, 0x1c803e30
	s_addc_u32 s7, s15, 0
	v_writelane_b32 v254, s6, 15
	s_nop 1
	v_writelane_b32 v254, s7, 16
	s_add_u32 s6, s14, 0x1c803e14
	s_addc_u32 s7, s15, 0
	v_writelane_b32 v254, s6, 17
	s_nop 1
	v_writelane_b32 v254, s7, 18
	s_add_u32 s6, s14, 0x1c803e34
	s_addc_u32 s7, s15, 0
	v_writelane_b32 v254, s6, 19
	s_nop 1
	v_writelane_b32 v254, s7, 20
	s_add_u32 s6, s14, 0x1c803e18
	s_addc_u32 s7, s15, 0
	v_writelane_b32 v254, s6, 21
	s_nop 1
	v_writelane_b32 v254, s7, 22
	s_add_u32 s6, s14, 0x1c803e38
	s_addc_u32 s7, s15, 0
	v_writelane_b32 v254, s6, 23
	s_nop 1
	v_writelane_b32 v254, s7, 24
	s_add_u32 s6, s14, 0x1c803e1c
	s_addc_u32 s7, s15, 0
	v_writelane_b32 v254, s6, 25
	s_nop 1
	v_writelane_b32 v254, s7, 26
	s_add_u32 s6, s14, 0x1c803e3c
	s_addc_u32 s7, s15, 0
	v_writelane_b32 v254, s6, 27
	s_nop 1
	v_writelane_b32 v254, s7, 28
	s_load_dword s6, s[0:1], 0xc0
	s_waitcnt lgkmcnt(0)
; DI int hw_lane() { int l; asm volatile("v_mbcnt_lo_u32_b32 %0, -1, 0\n\tv_mbcnt_hi_u32_b32 %0, -1, %0" : "=v"(l)); return l; }
; #define PH_TID() const int tid = wave0 * 64 + hw_lane(), lane = tid & 63, wave = wave0
; __global__ void __launch_bounds__(512, 2) trunk_fwd(Args a_) {
;     ...
;     for (int ph = ph_lo; ph < ph_hi; ++ph) {
;         const int spx = ph == 0 ? 9 : (ph - 1) % NSP;
;         for (int rep = 0; rep < (((DUPM >> spx) & 1u) ? 2 : 1); ++rep) {
;         if (rep > 0 && coop) xcd_barrier(bar, wave0 * 64 + hw_lane());
;         AP a = (AP)__builtin_amdgcn_kernarg_segment_ptr(); asm volatile("" : "+s"(a));
;     ...
;         int G = gridDim.x, bx = blockIdx.x; asm volatile("" : "+s"(G), "+s"(bx));
;         const int vcu = (G % 8 == 0) ? (bx % 8) * (G / 8) + bx / 8 : bx;
;         unsigned char* ws = a->ws;
;         if (ph == 0) {
;             if (PHM & 512u) { PH_TID(); prologue(a, lds, tid, lane, wave, vcu, G); }
;         } else {
;             const int l = (ph - 1) / NSP, sp = (ph - 1) % NSP;
;             unsigned char* wl = ws + WS_W + (size_t)l * W_LAYER;
	s_mul_i32 s59, s2, s6
	s_add_i32 s2, s82, 0x80
	v_writelane_b32 v254, s2, 29
	s_mul_i32 s2, s4, 0x180
	s_mul_hi_u32 s6, s4, 0x180
	s_add_u32 s8, s2, 0x13000020
	s_addc_u32 s9, s6, 0
	v_writelane_b32 v254, s8, 30
	s_mul_hi_u32 s2, s4, 0x18000
	s_add_i32 s68, 0, 0x23400
	v_writelane_b32 v254, s9, 31
	v_writelane_b32 v254, s2, 32
	s_mul_i32 s2, s4, 0x18000
	v_writelane_b32 v254, s2, 33
	s_add_i32 s2, s5, 0xffffff60
	v_writelane_b32 v254, s2, 34
	s_add_i32 s2, 0, 0x20400
	v_writelane_b32 v254, s2, 35
	s_add_i32 s2, 0, 0x917c
	v_writelane_b32 v254, s2, 36
	v_cmp_eq_u32_e64 s[4:5], 0, v0
	s_mov_b32 s8, 0
	s_mov_b32 s2, s58
	v_writelane_b32 v254, s4, 37
	s_nop 1
	v_writelane_b32 v254, s5, 38
	s_mov_b64 s[4:5], 0
	v_writelane_b32 v254, s4, 39
	s_nop 1
	v_writelane_b32 v254, s5, 40
	v_writelane_b32 v254, s79, 41
	v_writelane_b32 v254, s0, 42
	s_nop 1
	v_writelane_b32 v254, s1, 43
	v_writelane_b32 v254, s2, 44
	s_nop 1
	v_writelane_b32 v254, s3, 45
	v_writelane_b32 v254, s62, 46
	s_nop 1
	v_writelane_b32 v254, s63, 47
	v_writelane_b32 v254, s66, 48
	s_nop 1
	v_writelane_b32 v254, s67, 49
	v_writelane_b32 v254, s82, 50
	v_writelane_b32 v254, s54, 51
	s_nop 1
	v_writelane_b32 v254, s55, 52
	v_writelane_b32 v254, s56, 53
	s_nop 1
	v_writelane_b32 v254, s57, 54
	v_writelane_b32 v254, s59, 55
	s_branch .LBB0_20

; DI float bf2f(unsigned short u) { return __uint_as_float((unsigned)u << 16); }
; #define ATT_LBAR() asm volatile("s_waitcnt lgkmcnt(0)\n\ts_barrier" ::: "memory")
; template <int MODE> DI void attn_unit(int b, int qb, const bf16* Qb, int qpitch, const bf16* Kb, int kpitch, const bf16* VT, bf16* O, float* ssq, ...
;     ...
;     v8s qr[ND];
; #pragma unroll
;     for (int d0 = 0; d0 < ND; ++d0) qr[d0] = *(const v8s*)(Qb + (rowbase + q) * qpitch + 16 * d0 + 8 * hi);
;     const int kt_lo = (MODE == 0) ? (4 * qb - 2 > 0 ? 4 * qb - 2 : 0) : 0, kt_hi = 4 * qb + 3;
;     v4u kreg0, kreg1 = {}, vreg; float freg = 0.f;
;     const int krow0 = tid / PCS, kc0 = tid % PCS, krow1 = (tid + 512) / PCS, kc1 = (tid + 512) % PCS;
;     const int vd = tid >> 3, vc = tid & 7;
;     ...
;     constexpr bool REV = (MODE == 1);
;     const int ntile = kt_hi - kt_lo + 1;
;     float qn = 0.f;
;     if (REV) {
; #pragma unroll
;         for (int d0 = 0; d0 < ND; ++d0)
; #pragma unroll
;             for (int j = 0; j < 8; ++j) { const float f = bf2f((unsigned short)qr[d0][j]); qn += f * f; }
;         qn += __shfl_xor(qn, 32); qn = sqrtf(qn) * 1.01f;
;     }
;     ATT_LOAD(REV ? kt_hi : kt_lo); ATT_STORE(0);
;     ATT_LBAR();
;     float m = (MODE == 0) ? aux2[0] * LOG2E : NEGBIG;
;     float lsum = (MODE == 0 && hi == 0) ? 1.f : 0.f;
;     v16f o0 = {}, o1 = {};
;     int buf = 0;
;     bool seen = false;
;     for (int it = 0; it < ntile; ++it) {
;         const int kt = REV ? kt_hi - it : kt_lo + it;
;         const bool more = it + 1 < ntile;
;         if (more) ATT_LOAD(REV ? kt - 1 : kt + 1);
.LBB0_457:
	s_and_b64 s[18:19], s[22:23], exec
	s_cselect_b32 s24, s58, s36
	s_lshl_b32 s69, s24, 8
	s_add_i32 s59, s69, s3
	v_or_b32_e32 v64, s59, v119
	v_lshl_add_u64 v[182:183], s[12:13], 0, v[64:65]
	v_mad_u64_u32 v[0:1], s[18:19], v182, s86, v[160:161]
	s_waitcnt lgkmcnt(0)
	s_barrier
	v_mad_i32_i24 v1, v183, s86, v1
	global_load_dwordx4 v[66:69], v[0:1], off offset:32
	global_load_dwordx4 v[70:73], v[0:1], off offset:64
	global_load_dwordx4 v[74:77], v[0:1], off offset:96
	global_load_dwordx4 v[78:81], v[0:1], off offset:128
	global_load_dwordx4 v[82:85], v[0:1], off offset:160
	global_load_dwordx4 v[86:89], v[0:1], off
	global_load_dwordx4 v[90:93], v[162:163], off
	s_waitcnt vmcnt(12)
	v_mov_b32_e32 v94, v65
	v_mov_b32_e32 v95, v65
	v_mov_b32_e32 v96, v65
	v_mov_b32_e32 v97, v65
	s_and_saveexec_b64 s[18:19], s[38:39]
	s_cbranch_execz .Lmla_p1
	global_load_dwordx4 v[94:97], v[164:165], off
	global_load_dwordx4 v[36:39], v[178:179], off
.Lmla_p1:
	s_or_b64 exec, exec, s[18:19]
	global_load_dwordx4 v[98:101], v[166:167], off
	global_load_dwordx4 v[32:35], v[180:181], off
	s_waitcnt vmcnt(0)
	ds_write_b128 v206, v[90:93]
	v_add_u32_e32 v159, 0x3400, v206
	ds_write_b128 v159, v[32:35]
	s_and_saveexec_b64 s[18:19], s[38:39]
	s_cbranch_execz .Lmla_p2
	ds_write_b128 v207, v[94:97]
	v_add_u32_e32 v159, 0x3400, v207
	ds_write_b128 v159, v[36:39]
.Lmla_p2:
	s_or_b64 exec, exec, s[18:19]
	v_add_u32_e32 v0, 0x6800, v192
	ds_write2_b64 v0, v[98:99], v[100:101] offset1:1
	s_waitcnt lgkmcnt(0)
	s_barrier
	v_mov_b32_e32 v14, v65
	v_mov_b32_e32 v15, v65
	s_lshl_b32 s60, s24, 2
	v_mov_b32_e32 v0, v65
	v_mov_b32_e32 v1, v65
	v_mov_b32_e32 v2, v65
	v_mov_b32_e32 v3, v65
	v_mov_b32_e32 v4, v65
	v_mov_b32_e32 v5, v65
	v_mov_b32_e32 v6, v65
	v_mov_b32_e32 v7, v65
	v_mov_b32_e32 v8, v65
	v_mov_b32_e32 v9, v65
	v_mov_b32_e32 v10, v65
	v_mov_b32_e32 v11, v65
	v_mov_b32_e32 v12, v65
	v_mov_b32_e32 v13, v65
	v_mov_b64_e32 v[30:31], v[14:15]
	s_xor_b64 s[18:19], s[22:23], -1
	s_add_i32 s60, s60, 4
	s_or_b32 s61, s59, 31
	s_addk_i32 s69, 0x100
	s_mov_b32 s72, 0
	v_mov_b32_e32 v157, 0xf149f2ca
	v_mov_b32_e32 v155, 0
	s_mov_b32 s74, 1
	v_lshl_add_u64 v[184:185], v[180:181], 0, s[80:81]
	v_lshl_add_u64 v[186:187], v[178:179], 0, s[80:81]
	v_mov_b64_e32 v[188:189], v[176:177]
	v_mov_b64_e32 v[28:29], v[12:13]
	v_mov_b64_e32 v[26:27], v[10:11]
	v_mov_b64_e32 v[24:25], v[8:9]
	v_mov_b64_e32 v[22:23], v[6:7]
	v_mov_b64_e32 v[20:21], v[4:5]
	v_mov_b64_e32 v[18:19], v[2:3]
	v_mov_b64_e32 v[16:17], v[0:1]
	s_mov_b32 s75, 0
	s_mov_b32 s98, 0x680000
	s_mov_b32 s99, 0x8a3400
	s_mov_b32 s100, 0x190b800
	s_mov_b32 s101, 0
	s_cmp_lt_u32 s33, 4
	s_cbranch_scc1 .Lmla_loop
	s_barrier
.Lmla_loop:
	s_add_i32 s24, s74, 1
	s_cmp_lt_u32 s24, s60
	s_cselect_b64 s[22:23], -1, 0
	s_cbranch_scc0 .Lmla_nok
	global_load_dwordx4 v[90:93], v[184:185], off
	s_and_saveexec_b64 s[24:25], s[38:39]
	s_cbranch_execz .Lmla_k1
	global_load_dwordx4 v[94:97], v[186:187], off

; #define LAS __attribute__((address_space(3)))
; DI int crow(int r, int hi) { return (r & 3) + 8 * (r >> 2) + 4 * hi; }
; template <int MODE> DI void attn_unit(int b, int qb, const bf16* Qb, int qpitch, const bf16* Kb, int kpitch, const bf16* VT, bf16* O, float* ssq, ...
;     ...
;         if (more) ATT_LOAD(REV ? kt - 1 : kt + 1);
;         const int k0 = 64 * kt;
;         const bool active = (k0 <= qw0 + 31) && (MODE != 0 || k0 + 63 >= qw0 - 127);
;         if (active) {
;             const LAS unsigned char* kb = lds + KOFF + buf * KSZ + r32 * PK + 16 * hi;
;             v16f p0, p1;
; #pragma unroll
;             for (int d0 = 0; d0 < ND; ++d0) {
;                 const v8s ka = *(const LAS v8s*)(kb + 32 * d0), kb2 = *(const LAS v8s*)(kb + 32 * PK + 32 * d0);
;                 if (d0 == 0) { p0 = MFMA32(ka, qr[0], (v16f){}); p1 = MFMA32(kb2, qr[0], (v16f){}); }
;                 else { p0 = MFMA32(ka, qr[d0], p0); p1 = MFMA32(kb2, qr[d0], p1); }
;             }
;             asm volatile("s_nop 15\n\ts_nop 7" : "+v"(p0), "+v"(p1));
;             if (MODE == 1) {
;                 const LAS float* fb = (const LAS float*)(lds + FOFF + buf * 256);
; #pragma unroll
;                 for (int g = 0; g < 4; ++g) {
;                     const v4f f0 = *(const LAS v4f*)(fb + 8 * g + 4 * hi), f1 = *(const LAS v4f*)(fb + 32 + 8 * g + 4 * hi);
; #pragma unroll
;                     for (int i = 0; i < 4; ++i) { p0[4 * g + i] += f0[i]; p1[4 * g + i] += f1[i]; }
;                 }
;             }
;             if (MODE == 0) {
;                 const LAS float* tb = MS + (223 - q + k0 + 4 * hi);
; #pragma unroll
;                 for (int r = 0; r < 16; ++r) { p0[r] += tb[(r & 3) + 8 * (r >> 2)]; p1[r] += tb[32 + (r & 3) + 8 * (r >> 2)]; }
;             } else if (k0 + 63 > qw0) {
; #pragma unroll
;                 for (int r = 0; r < 16; ++r) {
;                     const int kv = k0 + crow(r, hi);
;                     if (kv > q) p0[r] = NEGBIG;
;                     if (kv + 32 > q) p1[r] = NEGBIG;
;                 }
;             }
;     ...
;             const LAS unsigned char* vb = lds + VOFF + buf * VSZ + r32 * 136 + 8 * hi;
; #pragma unroll
;             for (int s4 = 0; s4 < 4; ++s4) {
;                 v4u pw;
;                 if (s4 == 0) { pw.x = pk2(p0[0], p0[1]); pw.y = pk2(p0[2], p0[3]); pw.z = pk2(p0[4], p0[5]); pw.w = pk2(p0[6], p0[7]); }
.Lmla_nok:
	s_cmp_lt_u32 s74, s60
	s_cbranch_scc0 .Lmla_nov
	global_load_dwordx4 v[98:101], v[188:189], off
.Lmla_nov:
	s_cmp_eq_u32 s101, 0
	s_cbranch_scc1 .Lmla_nopv
	s_lshr_b32 s24, s100, 8
	s_and_b32 s24, s24, 0xffffff00
	v_add_u32_e32 v41, s24, v195
	v_add_u32_e32 v62, 0x1000, v41
	ds_read2_b64 v[50:53], v41 offset1:2
	ds_read2_b64 v[54:57], v41 offset0:4 offset1:6
	ds_read2_b64 v[58:61], v62 offset0:32 offset1:34
	s_waitcnt lgkmcnt(2)
	v_mfma_f32_32x32x16_bf16 v[0:15], v[50:53], v[42:45], v[0:15]
	s_waitcnt lgkmcnt(0)
	v_mfma_f32_32x32x16_bf16 v[16:31], v[58:61], v[42:45], v[16:31]
	ds_read2_b64 v[42:45], v62 offset0:36 offset1:38
	v_mfma_f32_32x32x16_bf16 v[0:15], v[54:57], v[46:49], v[0:15]
	s_waitcnt lgkmcnt(0)
	v_mfma_f32_32x32x16_bf16 v[16:31], v[42:45], v[46:49], v[16:31]
	ds_read2_b64 v[42:45], v41 offset0:8 offset1:10
	ds_read2_b64 v[46:49], v62 offset0:40 offset1:42
	s_waitcnt lgkmcnt(1)
	v_mfma_f32_32x32x16_bf16 v[0:15], v[42:45], v[36:39], v[0:15]
	s_waitcnt lgkmcnt(0)
	v_mfma_f32_32x32x16_bf16 v[16:31], v[46:49], v[36:39], v[16:31]
	ds_read2_b64 v[36:39], v41 offset0:12 offset1:14
	ds_read2_b64 v[42:45], v62 offset0:44 offset1:46
	s_waitcnt lgkmcnt(1)
	v_mfma_f32_32x32x16_bf16 v[0:15], v[36:39], v[32:35], v[0:15]
	s_waitcnt lgkmcnt(0)
	v_mfma_f32_32x32x16_bf16 v[16:31], v[42:45], v[32:35], v[16:31]
.Lmla_nopv:
	s_cmp_gt_u32 s72, s61
	s_cbranch_scc1 .Lmla_noqk
	s_and_b32 s24, s98, 0xffff
	v_add_u32_e32 v153, s24, v193
	ds_read_b128 v[32:35], v153
	ds_read_b128 v[36:39], v153 offset:32
	ds_read_b128 v[40:43], v153 offset:64
	ds_read_b128 v[44:47], v153 offset:96
	ds_read_b128 v[210:213], v153 offset:128
	ds_read_b128 v[236:239], v153 offset:160
	s_waitcnt lgkmcnt(5)
	v_mfma_f32_32x32x16_bf16 v[48:63], v[32:35], v[86:89], 0
	ds_read_b128 v[32:35], v153 offset:6656
	s_waitcnt lgkmcnt(5)
	v_mfma_f32_32x32x16_bf16 v[48:63], v[36:39], v[66:69], v[48:63]
	s_waitcnt lgkmcnt(4)
	v_mfma_f32_32x32x16_bf16 v[48:63], v[40:43], v[70:73], v[48:63]
	s_waitcnt lgkmcnt(3)
	v_mfma_f32_32x32x16_bf16 v[48:63], v[44:47], v[74:77], v[48:63]
	s_waitcnt lgkmcnt(2)
	v_mfma_f32_32x32x16_bf16 v[48:63], v[210:213], v[78:81], v[48:63]
	ds_read_b128 v[210:213], v153 offset:6688
	s_waitcnt lgkmcnt(2)
	v_mfma_f32_32x32x16_bf16 v[48:63], v[236:239], v[82:85], v[48:63]
	ds_read_b128 v[236:239], v153 offset:6720
	s_waitcnt lgkmcnt(2)
	v_mfma_f32_32x32x16_bf16 v[32:47], v[32:35], v[86:89], 0
	s_waitcnt lgkmcnt(1)
	v_mfma_f32_32x32x16_bf16 v[32:47], v[210:213], v[66:69], v[32:47]
	ds_read_b128 v[210:213], v153 offset:6752
	s_waitcnt lgkmcnt(1)
	v_mfma_f32_32x32x16_bf16 v[32:47], v[236:239], v[70:73], v[32:47]
	ds_read_b128 v[236:239], v153 offset:6784
	s_waitcnt lgkmcnt(1)
	v_mfma_f32_32x32x16_bf16 v[32:47], v[210:213], v[74:77], v[32:47]
	ds_read_b128 v[210:213], v153 offset:6816
	s_waitcnt lgkmcnt(1)
	v_mfma_f32_32x32x16_bf16 v[32:47], v[236:239], v[78:81], v[32:47]
	s_waitcnt lgkmcnt(0)
	v_mfma_f32_32x32x16_bf16 v[32:47], v[210:213], v[82:85], v[32:47]
.Lmla_noqk:
	s_barrier
	s_cmp_gt_u32 s72, s61
	s_cbranch_scc1 .Lmla_inactive
	s_nop 7
	s_nop 3
	s_add_i32 s24, s72, 63
	s_cmp_le_u32 s24, s59
	s_cbranch_scc1 .LBB0_472
	v_add_u32_e32 v153, s72, v194
	v_add_u32_e32 v159, 32, v153
	v_cmp_le_u32_e32 vcc, v159, v64
	v_add_u32_e32 v159, 33, v153
	s_nop 6
	v_cndmask_b32_e32 v32, v234, v32, vcc
	v_cmp_lt_u32_e32 vcc, v153, v64
	s_nop 1
	v_cndmask_b32_e32 v49, v234, v49, vcc
	v_cmp_le_u32_e32 vcc, v153, v64
	s_nop 1
	v_cndmask_b32_e32 v48, v234, v48, vcc
	v_cmp_le_u32_e32 vcc, v159, v64
	v_add_u32_e32 v159, 2, v153
	s_nop 0
	v_cndmask_b32_e32 v33, v234, v33, vcc
	v_cmp_le_u32_e32 vcc, v159, v64
	v_add_u32_e32 v159, 34, v153
	s_nop 0
	v_cndmask_b32_e32 v50, v234, v50, vcc
	v_cmp_le_u32_e32 vcc, v159, v64
	v_add_u32_e32 v159, 3, v153
	s_nop 0
	v_cndmask_b32_e32 v34, v234, v34, vcc
	v_cmp_le_u32_e32 vcc, v159, v64
	v_add_u32_e32 v159, 35, v153
	s_nop 0
	v_cndmask_b32_e32 v51, v234, v51, vcc
	v_cmp_le_u32_e32 vcc, v159, v64
	v_add_u32_e32 v159, 8, v153
	s_nop 0
	v_cndmask_b32_e32 v35, v234, v35, vcc
	v_cmp_le_u32_e32 vcc, v159, v64
	v_add_u32_e32 v159, 40, v153
	s_nop 0
	v_cndmask_b32_e32 v52, v234, v52, vcc
	v_cmp_le_u32_e32 vcc, v159, v64
	v_add_u32_e32 v159, 9, v153
	s_nop 0
	v_cndmask_b32_e32 v36, v234, v36, vcc
	v_cmp_le_u32_e32 vcc, v159, v64
	v_add_u32_e32 v159, 41, v153
	s_nop 0
	v_cndmask_b32_e32 v53, v234, v53, vcc
	v_cmp_le_u32_e32 vcc, v159, v64
	v_add_u32_e32 v159, 10, v153
	s_nop 0
	v_cndmask_b32_e32 v37, v234, v37, vcc
	v_cmp_le_u32_e32 vcc, v159, v64
	v_add_u32_e32 v159, 42, v153
	s_nop 0
	v_cndmask_b32_e32 v54, v234, v54, vcc
	v_cmp_le_u32_e32 vcc, v159, v64
	v_add_u32_e32 v159, 11, v153
	s_nop 0
	v_cndmask_b32_e32 v38, v234, v38, vcc
	v_cmp_le_u32_e32 vcc, v159, v64
	v_add_u32_e32 v159, 43, v153
	s_nop 0
	v_cndmask_b32_e32 v55, v234, v55, vcc
	v_cmp_le_u32_e32 vcc, v159, v64
	v_add_u32_e32 v159, 16, v153
	s_nop 0
	v_cndmask_b32_e32 v39, v234, v39, vcc
	v_cmp_le_u32_e32 vcc, v159, v64
	v_add_u32_e32 v159, 48, v153
	s_nop 0
	v_cndmask_b32_e32 v56, v234, v56, vcc
	v_cmp_le_u32_e32 vcc, v159, v64
	v_add_u32_e32 v159, 17, v153
	s_nop 0
	v_cndmask_b32_e32 v40, v234, v40, vcc
	v_cmp_le_u32_e32 vcc, v159, v64
	v_add_u32_e32 v159, 49, v153
	s_nop 0
	v_cndmask_b32_e32 v57, v234, v57, vcc
	v_cmp_le_u32_e32 vcc, v159, v64
	v_add_u32_e32 v159, 18, v153
	s_nop 0
	v_cndmask_b32_e32 v41, v234, v41, vcc
	v_cmp_le_u32_e32 vcc, v159, v64
	v_add_u32_e32 v159, 50, v153
	s_nop 0
	v_cndmask_b32_e32 v58, v234, v58, vcc
	v_cmp_le_u32_e32 vcc, v159, v64
	v_add_u32_e32 v159, 19, v153
	s_nop 0
	v_cndmask_b32_e32 v42, v234, v42, vcc
	v_cmp_le_u32_e32 vcc, v159, v64
	v_add_u32_e32 v159, 51, v153
	s_nop 0
	v_cndmask_b32_e32 v59, v234, v59, vcc
	v_cmp_le_u32_e32 vcc, v159, v64
	v_add_u32_e32 v159, 24, v153
	s_nop 0
	v_cndmask_b32_e32 v43, v234, v43, vcc
	v_cmp_le_u32_e32 vcc, v159, v64
	v_add_u32_e32 v159, 56, v153
	s_nop 0
	v_cndmask_b32_e32 v60, v234, v60, vcc
	v_cmp_le_u32_e32 vcc, v159, v64
	v_add_u32_e32 v159, 25, v153
	s_nop 0
	v_cndmask_b32_e32 v44, v234, v44, vcc
	v_cmp_le_u32_e32 vcc, v159, v64
	v_add_u32_e32 v159, 57, v153
	s_nop 0
	v_cndmask_b32_e32 v61, v234, v61, vcc
	v_cmp_le_u32_e32 vcc, v159, v64
	v_add_u32_e32 v159, 26, v153
	s_nop 0
	v_cndmask_b32_e32 v45, v234, v45, vcc
	v_cmp_le_u32_e32 vcc, v159, v64
	v_add_u32_e32 v159, 58, v153
	s_nop 0
	v_cndmask_b32_e32 v62, v234, v62, vcc
	v_cmp_le_u32_e32 vcc, v159, v64
	v_add_u32_e32 v159, 27, v153
	v_add_u32_e32 v153, 59, v153
	v_cndmask_b32_e32 v46, v234, v46, vcc
	v_cmp_le_u32_e32 vcc, v159, v64
	s_nop 1
	v_cndmask_b32_e32 v63, v234, v63, vcc
	v_cmp_le_u32_e32 vcc, v153, v64
	s_nop 1
	v_cndmask_b32_e32 v47, v234, v47, vcc

; DI float max3f(float a, float b, float c) { float r; asm("v_max3_f32 %0, %1, %2, %3" : "=v"(r) : "v"(a), "v"(b), "v"(c)); return r; }
; DI float max2f(float a, float b) { float r; asm("v_max_f32_e32 %0, %1, %2" : "=v"(r) : "v"(a), "v"(b)); return r; }
; template <int MODE> DI void attn_unit(int b, int qb, const bf16* Qb, int qpitch, const bf16* Kb, int kpitch, const bf16* VT, bf16* O, float* ssq, ...
;     ...
;             float rm;
;             { float ma = max3f(p0[0], p0[1], p1[0]), mb = max3f(p0[2], p0[3], p1[1]); ma = max3f(ma, p1[2], p1[3]);
; #pragma unroll
;               for (int r = 4; r < 16; r += 4) { ma = max3f(ma, p0[r], p0[r + 1]); mb = max3f(mb, p0[r + 2], p0[r + 3]); ma = max3f(ma, p1[r], p1[r + 1]); mb = max3f(mb, p1[r + 2], p1[r + 3]); }
;               rm = max2f(ma, mb); }
;             { const auto rr = __builtin_amdgcn_permlane32_swap(__float_as_uint(rm), __float_as_uint(rm), false, false); rm = max2f(__uint_as_float(rr[0]), __uint_as_float(rr[1])); }
;             const float mn = max2f(m, rm), corr = __builtin_amdgcn_exp2f(m - mn);
;             m = mn;
;             float rs = 0.f;
; #pragma unroll
;             for (int r = 0; r < 16; ++r) { p0[r] = __builtin_amdgcn_exp2f(p0[r] - mn); p1[r] = __builtin_amdgcn_exp2f(p1[r] - mn); rs += p0[r] + p1[r]; }
;             lsum = lsum * corr + rs;
;             if (__any(corr != 1.0f)) {
; #pragma unroll
;                 for (int r = 0; r < 16; ++r) { o0[r] *= corr; o1[r] *= corr; }
;             }
;             seen = true;
.LBB0_474:
	v_sub_f32_e32 v48, v48, v153
	v_sub_f32_e32 v32, v32, v153
	v_exp_f32_e32 v48, v48
	v_exp_f32_e32 v32, v32
	v_sub_f32_e32 v49, v49, v153
	v_sub_f32_e32 v33, v33, v153
	v_exp_f32_e32 v49, v49
	v_exp_f32_e32 v33, v33
	v_sub_f32_e32 v50, v50, v153
	v_sub_f32_e32 v34, v34, v153
	v_exp_f32_e32 v50, v50
	v_exp_f32_e32 v34, v34
	v_sub_f32_e32 v51, v51, v153
	v_sub_f32_e32 v35, v35, v153
	v_exp_f32_e32 v51, v51
	v_exp_f32_e32 v35, v35
	v_add_f32_e32 v157, v32, v48
	v_add_f32_e32 v157, 0, v157
	v_add_f32_e32 v159, v33, v49
	v_add_f32_e32 v157, v159, v157
	v_add_f32_e32 v159, v34, v50
	v_add_f32_e32 v157, v159, v157
	v_add_f32_e32 v159, v35, v51
	v_sub_f32_e32 v52, v52, v153
	v_sub_f32_e32 v36, v36, v153
	v_add_f32_e32 v157, v159, v157
	v_exp_f32_e32 v52, v52
	v_exp_f32_e32 v159, v36
	v_sub_f32_e32 v53, v53, v153
	v_sub_f32_e32 v37, v37, v153
	v_exp_f32_e32 v53, v53
	v_add_f32_e32 v36, v159, v52
	v_add_f32_e32 v36, v36, v157
	v_exp_f32_e32 v157, v37
	v_sub_f32_e32 v38, v38, v153
	v_sub_f32_e32 v39, v39, v153
	v_exp_f32_e32 v39, v39
	v_add_f32_e32 v37, v157, v53
	v_add_f32_e32 v36, v37, v36
	v_sub_f32_e32 v37, v54, v153
	v_exp_f32_e32 v37, v37
	v_exp_f32_e32 v54, v38
	v_sub_f32_e32 v40, v40, v153
	v_add_f32_e32 v38, v54, v37
	v_add_f32_e32 v36, v38, v36
	v_sub_f32_e32 v38, v55, v153
	v_exp_f32_e32 v38, v38
	s_nop 0
	v_add_f32_e32 v55, v39, v38
	v_add_f32_e32 v36, v55, v36
	v_sub_f32_e32 v55, v56, v153
	v_exp_f32_e32 v55, v55
	v_exp_f32_e32 v56, v40
	v_cvt_pk_bf16_f32 v39, v54, v39
	v_add_f32_e32 v40, v56, v55
	v_add_f32_e32 v36, v40, v36
	v_sub_f32_e32 v40, v57, v153
	v_exp_f32_e32 v57, v40
	v_sub_f32_e32 v40, v41, v153
	v_exp_f32_e32 v41, v40
	s_nop 0
	v_add_f32_e32 v40, v41, v57
	v_add_f32_e32 v36, v40, v36
	v_sub_f32_e32 v40, v58, v153
	v_exp_f32_e32 v58, v40
	v_sub_f32_e32 v40, v42, v153
	v_exp_f32_e32 v172, v40
	v_cvt_pk_bf16_f32 v42, v48, v49
	v_add_f32_e32 v40, v172, v58
	v_add_f32_e32 v36, v40, v36
	v_sub_f32_e32 v40, v59, v153
	v_exp_f32_e32 v59, v40
	v_sub_f32_e32 v40, v43, v153
	v_exp_f32_e32 v173, v40
	v_cvt_pk_bf16_f32 v43, v50, v51
	v_add_f32_e32 v40, v173, v59
	v_add_f32_e32 v36, v40, v36
	v_sub_f32_e32 v40, v60, v153
	v_exp_f32_e32 v60, v40
	v_sub_f32_e32 v40, v44, v153
	v_exp_f32_e32 v210, v40
	v_cvt_pk_bf16_f32 v44, v52, v53
	v_add_f32_e32 v40, v210, v60
	v_add_f32_e32 v36, v40, v36
	v_sub_f32_e32 v40, v61, v153
	v_exp_f32_e32 v61, v40
	v_sub_f32_e32 v40, v45, v153
	v_exp_f32_e32 v211, v40
	v_cvt_pk_bf16_f32 v45, v37, v38
	v_cvt_pk_bf16_f32 v48, v60, v61
	v_cvt_pk_bf16_f32 v37, v34, v35
	v_add_f32_e32 v40, v211, v61
	v_add_f32_e32 v36, v40, v36
	v_sub_f32_e32 v40, v62, v153
	v_exp_f32_e32 v62, v40
	v_sub_f32_e32 v40, v46, v153
	v_exp_f32_e32 v212, v40
	v_cvt_pk_bf16_f32 v46, v55, v57
	v_cvt_pk_bf16_f32 v38, v159, v157
	v_cvt_pk_bf16_f32 v34, v210, v211
	v_add_f32_e32 v40, v212, v62
	v_add_f32_e32 v36, v40, v36
	v_sub_f32_e32 v40, v63, v153
	v_exp_f32_e32 v63, v40
	v_sub_f32_e32 v40, v47, v153
	v_exp_f32_e32 v213, v40
	v_cvt_pk_bf16_f32 v47, v58, v59
	v_cvt_pk_bf16_f32 v49, v62, v63
	v_mov_b32_e32 v157, v153
	v_add_f32_e32 v40, v213, v63
	v_add_f32_e32 v40, v40, v36
	v_fmac_f32_e32 v40, v155, v190
	v_cvt_pk_bf16_f32 v36, v32, v33
	v_cvt_pk_bf16_f32 v32, v56, v41
	v_cvt_pk_bf16_f32 v33, v172, v173
	v_cvt_pk_bf16_f32 v35, v212, v213
	v_mov_b32_e32 v155, v40
	s_mov_b32 s101, 1
	s_branch .Lmla_store
.Lmla_inactive:
	s_mov_b32 s101, 0
.Lmla_store:
	s_and_b64 vcc, exec, s[22:23]
	s_cbranch_vccz .Lmla_nostk
	s_and_b32 s24, s100, 0xffff
	v_add3_u32 v159, s24, v170, v171
	s_waitcnt vmcnt(1)
	ds_write_b128 v159, v[90:93]
	s_and_saveexec_b64 s[22:23], s[38:39]
	s_cbranch_execz .Lmla_k1st
	v_add3_u32 v159, s24, v174, v191
	ds_write_b128 v159, v[94:97]

; #define LAS __attribute__((address_space(3)))
; template <int MODE> DI void attn_unit(int b, int qb, const bf16* Qb, int qpitch, const bf16* Kb, int kpitch, const bf16* VT, bf16* O, float* ssq, ...
;     ...
;         if (more) ATT_STORE(buf ^ 1);
;         if (REV) {
;             int vote = 0;
;             if (seen && kt > 0) { const float fb0 = ((const LAS float*)(lds + FOFF + buf * 256))[0]; const float kb = MS[32 + ((kt - 1) >> 1)]; vote = __all((qn * kb + fb0 - m) < -40.0f) ? 1 : 0; }
;             volatile LAS int* vt = (volatile LAS int*)(MS + 64) + (it & 1) * 8;
;             if (lane == 0) vt[wave] = vote;
;             __syncthreads();
;             const int stop = vt[0] & vt[1] & vt[2] & vt[3] & vt[4] & vt[5] & vt[6] & vt[7];
;             if (stop) break;
;         } else {
;             __syncthreads();
;         }
;         buf ^= 1;
;     }
;     ...
;     lsum += __shfl_xor(lsum, 32);
;     const float inv = 1.0f / lsum;
;     float sq = 0.f;
; #pragma unroll
;     for (int r = 0; r < 16; ++r) { o0[r] *= inv; o1[r] *= inv; sq += o0[r] * o0[r] + o1[r] * o1[r]; }
;     sq += __shfl_xor(sq, 32);
;     if (hi == 0) ssq[(rowbase + q) * 16] = sq;
.Lmla_nostk:
	s_cmp_lt_u32 s74, s60
	s_cbranch_scc0 .Lmla_nostv
	s_lshr_b32 s24, s99, 8
	s_and_b32 s24, s24, 0xffffff00
	v_add_u32_e32 v159, s24, v192
	s_waitcnt vmcnt(0)
	ds_write2_b64 v159, v[98:99], v[100:101] offset1:1
.Lmla_nostv:
	s_add_i32 s72, s72, 64
	s_add_i32 s74, s74, 1
	v_lshl_add_u64 v[188:189], v[188:189], 0, s[92:93]
	v_lshl_add_u64 v[186:187], v[186:187], 0, s[80:81]
	v_lshl_add_u64 v[184:185], v[184:185], 0, s[80:81]
	s_mov_b32 s24, s98
	s_mov_b32 s98, s99
	s_mov_b32 s99, s100
	s_mov_b32 s100, s24
	s_cmp_eq_u32 s69, s72
	s_waitcnt lgkmcnt(0)
	s_barrier
	s_cbranch_scc0 .Lmla_loop
	s_cmp_eq_u32 s101, 0
	s_cbranch_scc1 .Lmla_nopv2
	s_lshr_b32 s24, s100, 8
	s_and_b32 s24, s24, 0xffffff00
	v_add_u32_e32 v41, s24, v195
	v_add_u32_e32 v62, 0x1000, v41
	ds_read2_b64 v[50:53], v41 offset1:2
	ds_read2_b64 v[54:57], v41 offset0:4 offset1:6
	ds_read2_b64 v[58:61], v62 offset0:32 offset1:34
	s_waitcnt lgkmcnt(2)
	v_mfma_f32_32x32x16_bf16 v[0:15], v[50:53], v[42:45], v[0:15]
	s_waitcnt lgkmcnt(0)
	v_mfma_f32_32x32x16_bf16 v[16:31], v[58:61], v[42:45], v[16:31]
	ds_read2_b64 v[42:45], v62 offset0:36 offset1:38
	v_mfma_f32_32x32x16_bf16 v[0:15], v[54:57], v[46:49], v[0:15]
	s_waitcnt lgkmcnt(0)
	v_mfma_f32_32x32x16_bf16 v[16:31], v[42:45], v[46:49], v[16:31]
	ds_read2_b64 v[42:45], v41 offset0:8 offset1:10
	ds_read2_b64 v[46:49], v62 offset0:40 offset1:42
	s_waitcnt lgkmcnt(1)
	v_mfma_f32_32x32x16_bf16 v[0:15], v[42:45], v[36:39], v[0:15]
	s_waitcnt lgkmcnt(0)
	v_mfma_f32_32x32x16_bf16 v[16:31], v[46:49], v[36:39], v[16:31]
	ds_read2_b64 v[36:39], v41 offset0:12 offset1:14
	ds_read2_b64 v[42:45], v62 offset0:44 offset1:46
	s_waitcnt lgkmcnt(1)
	v_mfma_f32_32x32x16_bf16 v[0:15], v[36:39], v[32:35], v[0:15]
	s_waitcnt lgkmcnt(0)
	v_mfma_f32_32x32x16_bf16 v[16:31], v[42:45], v[32:35], v[16:31]
	s_nop 7
	s_nop 3
.Lmla_nopv2:
	s_cmp_gt_u32 s33, 3
	s_cbranch_scc1 .Lmla_done
	s_barrier
.Lmla_done:
.LBB0_477:
	v_and_b32_e32 v36, 64, v226
	v_xor_b32_e32 v32, 32, v226
	v_add_u32_e32 v33, 64, v36
	v_cmp_lt_i32_e32 vcc, v32, v33
	s_nop 1
	v_cndmask_b32_e32 v32, v226, v32, vcc
	v_lshlrev_b32_e32 v190, 2, v32
	ds_bpermute_b32 v32, v190, v155
	s_waitcnt lgkmcnt(0)
	v_add_f32_e32 v32, v155, v32
	v_div_scale_f32 v33, s[22:23], v32, v32, 1.0
	v_rcp_f32_e32 v34, v33
	v_div_scale_f32 v35, vcc, 1.0, v32, 1.0
	v_fma_f32 v37, -v33, v34, 1.0
	v_fmac_f32_e32 v34, v37, v34
	v_mul_f32_e32 v37, v35, v34
	v_fma_f32 v38, -v33, v37, v35
	v_fmac_f32_e32 v37, v38, v34
	v_fma_f32 v33, -v33, v37, v35
	v_div_fmas_f32 v33, v33, v34, v37
	v_div_fixup_f32 v38, v33, v32, 1.0
	v_pk_mul_f32 v[32:33], v[0:1], v[38:39] op_sel_hi:[1,0]
	v_pk_mul_f32 v[0:1], v[16:17], v[38:39] op_sel_hi:[1,0]
	v_pk_mul_f32 v[16:17], v[32:33], v[32:33]
	v_pk_mul_f32 v[2:3], v[2:3], v[38:39] op_sel_hi:[1,0]
	v_pk_fma_f32 v[40:41], v[0:1], v[0:1], v[16:17]
	v_pk_mul_f32 v[34:35], v[2:3], v[2:3]
	v_pk_mul_f32 v[16:17], v[18:19], v[38:39] op_sel_hi:[1,0]
	v_pk_mul_f32 v[18:19], v[4:5], v[38:39] op_sel_hi:[1,0]
	v_pk_fma_f32 v[42:43], v[16:17], v[16:17], v[34:35]
	v_add_f32_e32 v37, v40, v41
	v_pk_mul_f32 v[34:35], v[18:19], v[18:19]
	v_pk_mul_f32 v[4:5], v[20:21], v[38:39] op_sel_hi:[1,0]
	v_add_f32_e32 v37, v42, v37
	v_pk_fma_f32 v[44:45], v[4:5], v[4:5], v[34:35]
	v_pk_mul_f32 v[34:35], v[6:7], v[38:39] op_sel_hi:[1,0]
	v_add_f32_e32 v37, v43, v37
	v_pk_mul_f32 v[20:21], v[34:35], v[34:35]
	v_pk_mul_f32 v[6:7], v[22:23], v[38:39] op_sel_hi:[1,0]
	v_add_f32_e32 v37, v44, v37
	v_pk_fma_f32 v[46:47], v[6:7], v[6:7], v[20:21]
	v_pk_mul_f32 v[8:9], v[8:9], v[38:39] op_sel_hi:[1,0]
	v_add_f32_e32 v37, v45, v37
	v_pk_mul_f32 v[22:23], v[8:9], v[8:9]
	v_pk_mul_f32 v[20:21], v[24:25], v[38:39] op_sel_hi:[1,0]
	v_add_f32_e32 v37, v46, v37
	v_pk_fma_f32 v[48:49], v[20:21], v[20:21], v[22:23]
	v_pk_mul_f32 v[10:11], v[10:11], v[38:39] op_sel_hi:[1,0]
	v_add_f32_e32 v37, v47, v37
	v_pk_mul_f32 v[24:25], v[10:11], v[10:11]
	v_pk_mul_f32 v[22:23], v[26:27], v[38:39] op_sel_hi:[1,0]
	v_add_f32_e32 v37, v48, v37
	v_pk_fma_f32 v[50:51], v[22:23], v[22:23], v[24:25]
	v_pk_mul_f32 v[24:25], v[12:13], v[38:39] op_sel_hi:[1,0]
	v_add_f32_e32 v37, v49, v37
	v_pk_mul_f32 v[26:27], v[24:25], v[24:25]
	v_pk_mul_f32 v[12:13], v[28:29], v[38:39] op_sel_hi:[1,0]
	v_add_f32_e32 v37, v50, v37
	v_pk_fma_f32 v[28:29], v[12:13], v[12:13], v[26:27]
	v_pk_mul_f32 v[26:27], v[14:15], v[38:39] op_sel_hi:[1,0]
	v_add_f32_e32 v37, v51, v37
	v_pk_mul_f32 v[52:53], v[26:27], v[26:27]
	v_pk_mul_f32 v[14:15], v[30:31], v[38:39] op_sel_hi:[1,0]
	v_add_f32_e32 v28, v28, v37
	v_pk_fma_f32 v[30:31], v[14:15], v[14:15], v[52:53]
	v_add_f32_e32 v28, v29, v28
	v_add_f32_e32 v28, v30, v28
	v_add_f32_e32 v28, v31, v28
	ds_bpermute_b32 v29, v190, v28
	s_and_saveexec_b64 s[22:23], s[56:57]
	s_cbranch_execz .LBB0_456
	v_lshlrev_b64 v[30:31], 6, v[182:183]
	v_lshl_add_u64 v[30:31], s[16:17], 0, v[30:31]
	s_waitcnt lgkmcnt(0)
	v_add_f32_e32 v28, v28, v29
	global_store_dword v[30:31], v28, off
	s_branch .LBB0_456

; DI void prep_unit(AP a, int l, int unit, LAS unsigned char* lds, int tid, int lane, int wave) {
;     ...
;     for (int k = 0; k < 12; ++k) {
;         const int it = tid + 512 * k, c = it % 384, rg = it / 384;
;         const int src = c < 128 ? C_SWAV + c : C_FOXV + (c - 128);
;         unsigned short e[8];
; #pragma unroll
;         for (int j = 0; j < 8; ++j) e[j] = proj[(size_t)(t0 + 8 * rg + j) * NPROJ + src];
;         v4u w; w.x = e[0] | ((unsigned)e[1] << 16); w.y = e[2] | ((unsigned)e[3] << 16); w.z = e[4] | ((unsigned)e[5] << 16); w.w = e[6] | ((unsigned)e[7] << 16);
;         bf16* dst = c < 128 ? vts + ((size_t)(b * 2 + (c >> 6)) * 64 + (c & 63)) * SEQ : vtf + ((size_t)(b * 4 + ((c - 128) >> 6)) * 64 + ((c - 128) & 63)) * SEQ;
;         *(v4u*)(dst + s0 + 8 * rg) = w;
;     }
.LBB0_675:
	v_add_u32_e32 v8, s20, v162
	v_mul_hi_i32 v2, v8, s78
	v_lshrrev_b32_e32 v3, 31, v2
	v_ashrrev_i32_e32 v2, 6, v2
	v_add_u32_e32 v2, v2, v3
	v_mul_i32_i24_e32 v3, 0x180, v2
	v_sub_u32_e32 v3, v8, v3
	v_cmp_gt_i32_e32 vcc, s83, v3
	v_lshlrev_b32_e32 v2, 3, v2
	s_nop 0
	v_cndmask_b32_e64 v4, 0, 1, vcc
	v_lshlrev_b32_e32 v4, 9, v4
	v_sub_u32_e32 v4, 0x480, v4
	v_add_u32_e32 v64, v4, v3
	v_add_u32_e32 v4, s2, v2
	v_ashrrev_i32_e32 v5, 31, v4
	v_or_b32_e32 v12, 1, v4
	v_or_b32_e32 v14, 2, v4
	v_lshlrev_b64 v[10:11], 12, v[4:5]
	v_ashrrev_i32_e32 v13, 31, v12
	v_ashrrev_i32_e32 v15, 31, v14
	v_or_b32_e32 v16, 3, v4
	v_or_b32_e32 v18, 4, v4
	v_or_b32_e32 v20, 5, v4
	v_or_b32_e32 v22, 6, v4
	v_or_b32_e32 v4, 7, v4
	v_lshl_add_u64 v[6:7], v[64:65], 1, s[56:57]
	v_lshlrev_b64 v[12:13], 12, v[12:13]
	v_lshlrev_b64 v[14:15], 12, v[14:15]
	v_ashrrev_i32_e32 v17, 31, v16
	v_ashrrev_i32_e32 v19, 31, v18
	v_ashrrev_i32_e32 v21, 31, v20
	v_ashrrev_i32_e32 v23, 31, v22
	v_ashrrev_i32_e32 v5, 31, v4
	v_lshl_add_u64 v[10:11], v[6:7], 0, v[10:11]
	v_lshl_add_u64 v[12:13], v[6:7], 0, v[12:13]
	v_lshl_add_u64 v[14:15], v[6:7], 0, v[14:15]
	v_lshlrev_b64 v[16:17], 12, v[16:17]
	v_lshlrev_b64 v[18:19], 12, v[18:19]
	v_lshlrev_b64 v[20:21], 12, v[20:21]
	v_lshlrev_b64 v[22:23], 12, v[22:23]
	v_lshlrev_b64 v[4:5], 12, v[4:5]
	v_lshl_add_u64 v[16:17], v[6:7], 0, v[16:17]
	v_lshl_add_u64 v[18:19], v[6:7], 0, v[18:19]
	v_lshl_add_u64 v[20:21], v[6:7], 0, v[20:21]
	v_lshl_add_u64 v[22:23], v[6:7], 0, v[22:23]
	v_lshl_add_u64 v[6:7], v[6:7], 0, v[4:5]
	global_load_ushort v5, v[10:11], off
	global_load_ushort v9, v[12:13], off
	s_nop 0
	global_load_ushort v10, v[14:15], off
	global_load_ushort v11, v[16:17], off
	global_load_ushort v12, v[18:19], off
	global_load_ushort v13, v[20:21], off
	s_nop 0
	global_load_ushort v14, v[22:23], off
	global_load_ushort v15, v[6:7], off
	v_cmp_lt_i32_e32 vcc, s88, v3
	s_and_saveexec_b64 s[18:19], vcc
	s_xor_b64 s[18:19], exec, s[18:19]
	v_add_u32_e32 v4, 0xffffff80, v3
	v_lshrrev_b32_e32 v4, 6, v4
	v_add_u32_e32 v4, s7, v4
	s_or_saveexec_b64 s[18:19], s[18:19]
	v_mov_b64_e32 v[6:7], 0x16800000
	s_xor_b64 exec, exec, s[18:19]
	v_ashrrev_i32_e32 v4, 6, v3
	v_add_u32_e32 v4, s6, v4
	v_mov_b64_e32 v[6:7], 0x16000000
	s_or_b64 exec, exec, s[18:19]
	s_waitcnt vmcnt(0)
	v_perm_b32 v15, v15, v14, s89
	v_perm_b32 v14, v13, v12, s89
	v_perm_b32 v12, v9, v5, s89
	v_ashrrev_i32_e32 v5, 31, v4
	v_lshl_add_u64 v[6:7], s[90:91], 0, v[6:7]
	v_lshlrev_b64 v[4:5], 19, v[4:5]
	v_lshlrev_b32_e32 v3, 13, v3
	v_lshl_add_u64 v[4:5], v[6:7], 0, v[4:5]
	v_and_b32_e32 v64, 0x7e000, v3
	v_lshl_add_u64 v[4:5], v[4:5], 0, v[64:65]
	v_lshl_add_u64 v[4:5], s[16:17], 1, v[4:5]
	v_ashrrev_i32_e32 v3, 31, v2
	v_perm_b32 v13, v11, v10, s89
	v_lshl_add_u64 v[2:3], v[2:3], 1, v[4:5]
	global_store_dwordx4 v[2:3], v[12:15], off
	v_add_u32_e32 v2, 0x200, v8
	v_mul_hi_i32 v3, v2, s78
	v_lshrrev_b32_e32 v4, 31, v3
	v_ashrrev_i32_e32 v3, 6, v3
	v_add_u32_e32 v4, v3, v4
	v_mul_i32_i24_e32 v3, 0x180, v4
	v_sub_u32_e32 v3, v2, v3
	v_cmp_gt_i32_e32 vcc, s83, v3
	s_nop 1
	v_cndmask_b32_e64 v2, 0, 1, vcc
	v_lshlrev_b32_e32 v2, 9, v2
	v_sub_u32_e32 v2, 0x480, v2
	v_add_u32_e32 v64, v2, v3
	v_lshlrev_b32_e32 v2, 3, v4
	v_add_u32_e32 v4, s2, v2
	v_ashrrev_i32_e32 v5, 31, v4
	v_or_b32_e32 v12, 1, v4
	v_or_b32_e32 v14, 2, v4
	v_lshlrev_b64 v[10:11], 12, v[4:5]
	v_ashrrev_i32_e32 v13, 31, v12
	v_ashrrev_i32_e32 v15, 31, v14
	v_or_b32_e32 v16, 3, v4
	v_or_b32_e32 v18, 4, v4
	v_or_b32_e32 v20, 5, v4
	v_or_b32_e32 v22, 6, v4
	v_or_b32_e32 v4, 7, v4
	v_lshl_add_u64 v[6:7], v[64:65], 1, s[56:57]
	v_lshlrev_b64 v[12:13], 12, v[12:13]
	v_lshlrev_b64 v[14:15], 12, v[14:15]
	v_ashrrev_i32_e32 v17, 31, v16
	v_ashrrev_i32_e32 v19, 31, v18
	v_ashrrev_i32_e32 v21, 31, v20
	v_ashrrev_i32_e32 v23, 31, v22
	v_ashrrev_i32_e32 v5, 31, v4
	v_lshl_add_u64 v[10:11], v[6:7], 0, v[10:11]
	v_lshl_add_u64 v[12:13], v[6:7], 0, v[12:13]
	v_lshl_add_u64 v[14:15], v[6:7], 0, v[14:15]
	v_lshlrev_b64 v[16:17], 12, v[16:17]
	v_lshlrev_b64 v[18:19], 12, v[18:19]
	v_lshlrev_b64 v[20:21], 12, v[20:21]
	v_lshlrev_b64 v[22:23], 12, v[22:23]
	v_lshlrev_b64 v[4:5], 12, v[4:5]
	v_lshl_add_u64 v[16:17], v[6:7], 0, v[16:17]
	v_lshl_add_u64 v[18:19], v[6:7], 0, v[18:19]
	v_lshl_add_u64 v[20:21], v[6:7], 0, v[20:21]
	v_lshl_add_u64 v[22:23], v[6:7], 0, v[22:23]
	v_lshl_add_u64 v[6:7], v[6:7], 0, v[4:5]
	global_load_ushort v5, v[10:11], off
	global_load_ushort v9, v[12:13], off
	s_nop 0
	global_load_ushort v10, v[14:15], off
	global_load_ushort v11, v[16:17], off
	global_load_ushort v12, v[18:19], off
	global_load_ushort v13, v[20:21], off
	s_nop 0
	global_load_ushort v14, v[22:23], off
	global_load_ushort v15, v[6:7], off
	v_cmp_lt_i32_e32 vcc, s88, v3
	s_and_saveexec_b64 s[18:19], vcc
	s_xor_b64 s[18:19], exec, s[18:19]
	v_add_u32_e32 v4, 0xffffff80, v3
	v_lshrrev_b32_e32 v4, 6, v4
	v_add_u32_e32 v4, s7, v4
	s_or_saveexec_b64 s[18:19], s[18:19]
	v_mov_b64_e32 v[6:7], 0x16800000
	s_xor_b64 exec, exec, s[18:19]
	v_ashrrev_i32_e32 v4, 6, v3
	v_add_u32_e32 v4, s6, v4
	v_mov_b64_e32 v[6:7], 0x16000000
	s_or_b64 exec, exec, s[18:19]
	s_waitcnt vmcnt(0)
; DI void prep_unit(AP a, int l, int unit, LAS unsigned char* lds, int tid, int lane, int wave) {
;     ...
;     for (int k = 0; k < 12; ++k) {
;         const int it = tid + 512 * k, c = it % 384, rg = it / 384;
;         const int src = c < 128 ? C_SWAV + c : C_FOXV + (c - 128);
;         unsigned short e[8];
; #pragma unroll
;         for (int j = 0; j < 8; ++j) e[j] = proj[(size_t)(t0 + 8 * rg + j) * NPROJ + src];
;         v4u w; w.x = e[0] | ((unsigned)e[1] << 16); w.y = e[2] | ((unsigned)e[3] << 16); w.z = e[4] | ((unsigned)e[5] << 16); w.w = e[6] | ((unsigned)e[7] << 16);
;         bf16* dst = c < 128 ? vts + ((size_t)(b * 2 + (c >> 6)) * 64 + (c & 63)) * SEQ : vtf + ((size_t)(b * 4 + ((c - 128) >> 6)) * 64 + ((c - 128) & 63)) * SEQ;
;         *(v4u*)(dst + s0 + 8 * rg) = w;
;     }
	v_perm_b32 v15, v15, v14, s89
	v_perm_b32 v14, v13, v12, s89
	v_perm_b32 v12, v9, v5, s89
	v_ashrrev_i32_e32 v5, 31, v4
	v_lshl_add_u64 v[6:7], s[90:91], 0, v[6:7]
	v_lshlrev_b64 v[4:5], 19, v[4:5]
	v_lshlrev_b32_e32 v3, 13, v3
	v_lshl_add_u64 v[4:5], v[6:7], 0, v[4:5]
	v_and_b32_e32 v64, 0x7e000, v3
	v_lshl_add_u64 v[4:5], v[4:5], 0, v[64:65]
	v_lshl_add_u64 v[4:5], s[16:17], 1, v[4:5]
	v_ashrrev_i32_e32 v3, 31, v2
	v_perm_b32 v13, v11, v10, s89
	v_lshl_add_u64 v[2:3], v[2:3], 1, v[4:5]
	global_store_dwordx4 v[2:3], v[12:15], off
	v_add_u32_e32 v2, 0x400, v8
	v_mul_hi_i32 v3, v2, s78
	v_lshrrev_b32_e32 v4, 31, v3
	v_ashrrev_i32_e32 v3, 6, v3
	v_add_u32_e32 v4, v3, v4
	v_mul_i32_i24_e32 v3, 0x180, v4
	v_sub_u32_e32 v3, v2, v3
	v_cmp_gt_i32_e32 vcc, s83, v3
	s_nop 1
	v_cndmask_b32_e64 v2, 0, 1, vcc
	v_lshlrev_b32_e32 v2, 9, v2
	v_sub_u32_e32 v2, 0x480, v2
	v_add_u32_e32 v64, v2, v3
	v_lshlrev_b32_e32 v2, 3, v4
	v_add_u32_e32 v4, s2, v2
	v_ashrrev_i32_e32 v5, 31, v4
	v_or_b32_e32 v12, 1, v4
	v_or_b32_e32 v14, 2, v4
	v_lshlrev_b64 v[10:11], 12, v[4:5]
	v_ashrrev_i32_e32 v13, 31, v12
	v_ashrrev_i32_e32 v15, 31, v14
	v_or_b32_e32 v16, 3, v4
	v_or_b32_e32 v18, 4, v4
	v_or_b32_e32 v20, 5, v4
	v_or_b32_e32 v22, 6, v4
	v_or_b32_e32 v4, 7, v4
	v_lshl_add_u64 v[6:7], v[64:65], 1, s[56:57]
	v_lshlrev_b64 v[12:13], 12, v[12:13]
	v_lshlrev_b64 v[14:15], 12, v[14:15]
	v_ashrrev_i32_e32 v17, 31, v16
	v_ashrrev_i32_e32 v19, 31, v18
	v_ashrrev_i32_e32 v21, 31, v20
	v_ashrrev_i32_e32 v23, 31, v22
	v_ashrrev_i32_e32 v5, 31, v4
	v_lshl_add_u64 v[10:11], v[6:7], 0, v[10:11]
	v_lshl_add_u64 v[12:13], v[6:7], 0, v[12:13]
	v_lshl_add_u64 v[14:15], v[6:7], 0, v[14:15]
	v_lshlrev_b64 v[16:17], 12, v[16:17]
	v_lshlrev_b64 v[18:19], 12, v[18:19]
	v_lshlrev_b64 v[20:21], 12, v[20:21]
	v_lshlrev_b64 v[22:23], 12, v[22:23]
	v_lshlrev_b64 v[4:5], 12, v[4:5]
	v_lshl_add_u64 v[16:17], v[6:7], 0, v[16:17]
	v_lshl_add_u64 v[18:19], v[6:7], 0, v[18:19]
	v_lshl_add_u64 v[20:21], v[6:7], 0, v[20:21]
	v_lshl_add_u64 v[22:23], v[6:7], 0, v[22:23]
	v_lshl_add_u64 v[6:7], v[6:7], 0, v[4:5]
	global_load_ushort v5, v[10:11], off
	global_load_ushort v9, v[12:13], off
	s_nop 0
	global_load_ushort v10, v[14:15], off
	global_load_ushort v11, v[16:17], off
	global_load_ushort v12, v[18:19], off
	global_load_ushort v13, v[20:21], off
	s_nop 0
	global_load_ushort v14, v[22:23], off
	global_load_ushort v15, v[6:7], off
	v_cmp_lt_i32_e32 vcc, s88, v3
	s_and_saveexec_b64 s[18:19], vcc
	s_xor_b64 s[18:19], exec, s[18:19]
	v_add_u32_e32 v4, 0xffffff80, v3
	v_lshrrev_b32_e32 v4, 6, v4
	v_add_u32_e32 v4, s7, v4
	s_or_saveexec_b64 s[18:19], s[18:19]
	v_mov_b64_e32 v[6:7], 0x16800000
	s_xor_b64 exec, exec, s[18:19]
	v_ashrrev_i32_e32 v4, 6, v3
	v_add_u32_e32 v4, s6, v4
	v_mov_b64_e32 v[6:7], 0x16000000
	s_or_b64 exec, exec, s[18:19]
	s_waitcnt vmcnt(0)
	v_perm_b32 v15, v15, v14, s89
	v_perm_b32 v14, v13, v12, s89
	v_perm_b32 v12, v9, v5, s89
	v_ashrrev_i32_e32 v5, 31, v4
	v_lshl_add_u64 v[6:7], s[90:91], 0, v[6:7]
	v_lshlrev_b64 v[4:5], 19, v[4:5]
	v_lshlrev_b32_e32 v3, 13, v3
	v_lshl_add_u64 v[4:5], v[6:7], 0, v[4:5]
	v_and_b32_e32 v64, 0x7e000, v3
	v_lshl_add_u64 v[4:5], v[4:5], 0, v[64:65]
	v_lshl_add_u64 v[4:5], s[16:17], 1, v[4:5]
	v_ashrrev_i32_e32 v3, 31, v2
	v_perm_b32 v13, v11, v10, s89
	v_lshl_add_u64 v[2:3], v[2:3], 1, v[4:5]
	global_store_dwordx4 v[2:3], v[12:15], off
	v_add_u32_e32 v2, 0x600, v8
	v_mul_hi_i32 v3, v2, s78
	v_lshrrev_b32_e32 v4, 31, v3
	v_ashrrev_i32_e32 v3, 6, v3
	v_add_u32_e32 v4, v3, v4
	v_mul_i32_i24_e32 v3, 0x180, v4
	v_sub_u32_e32 v3, v2, v3
	v_cmp_gt_i32_e32 vcc, s83, v3
	s_nop 1
	v_cndmask_b32_e64 v2, 0, 1, vcc
	v_lshlrev_b32_e32 v2, 9, v2
	v_sub_u32_e32 v2, 0x480, v2
	v_add_u32_e32 v64, v2, v3
	v_lshlrev_b32_e32 v2, 3, v4
	v_add_u32_e32 v4, s2, v2
	v_ashrrev_i32_e32 v5, 31, v4
	v_or_b32_e32 v10, 1, v4
	v_or_b32_e32 v12, 2, v4
	v_or_b32_e32 v14, 3, v4
	v_lshlrev_b64 v[8:9], 12, v[4:5]
	v_ashrrev_i32_e32 v11, 31, v10
	v_ashrrev_i32_e32 v13, 31, v12
	v_ashrrev_i32_e32 v15, 31, v14
	v_or_b32_e32 v16, 4, v4
	v_or_b32_e32 v18, 5, v4
	v_or_b32_e32 v20, 6, v4
	v_or_b32_e32 v4, 7, v4
	v_lshl_add_u64 v[6:7], v[64:65], 1, s[56:57]
	v_lshlrev_b64 v[10:11], 12, v[10:11]
	v_lshlrev_b64 v[12:13], 12, v[12:13]
	v_lshlrev_b64 v[14:15], 12, v[14:15]
	v_ashrrev_i32_e32 v17, 31, v16
	v_ashrrev_i32_e32 v19, 31, v18
	v_ashrrev_i32_e32 v21, 31, v20
	v_ashrrev_i32_e32 v5, 31, v4
	v_lshl_add_u64 v[8:9], v[6:7], 0, v[8:9]
	v_lshl_add_u64 v[10:11], v[6:7], 0, v[10:11]
	v_lshl_add_u64 v[12:13], v[6:7], 0, v[12:13]
	v_lshl_add_u64 v[14:15], v[6:7], 0, v[14:15]
	v_lshlrev_b64 v[16:17], 12, v[16:17]
	v_lshlrev_b64 v[18:19], 12, v[18:19]
	v_lshlrev_b64 v[20:21], 12, v[20:21]
	v_lshlrev_b64 v[4:5], 12, v[4:5]
	v_lshl_add_u64 v[16:17], v[6:7], 0, v[16:17]
	v_lshl_add_u64 v[18:19], v[6:7], 0, v[18:19]
	v_lshl_add_u64 v[20:21], v[6:7], 0, v[20:21]
	v_lshl_add_u64 v[6:7], v[6:7], 0, v[4:5]
	global_load_ushort v5, v[8:9], off
	s_nop 0
	global_load_ushort v8, v[10:11], off
	global_load_ushort v9, v[12:13], off
	s_nop 0
	global_load_ushort v10, v[14:15], off
	global_load_ushort v11, v[16:17], off
	global_load_ushort v12, v[18:19], off
	global_load_ushort v13, v[20:21], off
	s_nop 0
	global_load_ushort v14, v[6:7], off
	v_cmp_lt_i32_e32 vcc, s88, v3
	s_and_saveexec_b64 s[18:19], vcc
	s_xor_b64 s[18:19], exec, s[18:19]
	v_add_u32_e32 v4, 0xffffff80, v3
	v_lshrrev_b32_e32 v4, 6, v4
	v_add_u32_e32 v4, s7, v4
	s_or_saveexec_b64 s[18:19], s[18:19]
	v_mov_b64_e32 v[6:7], 0x16800000
	s_xor_b64 exec, exec, s[18:19]
	s_cbranch_execz .LBB0_674
	v_ashrrev_i32_e32 v4, 6, v3
	v_add_u32_e32 v4, s6, v4
	v_mov_b64_e32 v[6:7], 0x16000000
	s_branch .LBB0_674

; #define LAS __attribute__((address_space(3)))
; __global__ void __launch_bounds__(512, 2) trunk_fwd(Args a_) {
;     extern __shared__ __attribute__((aligned(16))) unsigned char lds_raw[];
;     LAS unsigned char* lds = (LAS unsigned char*)lds_raw;
;     cg::grid_group grid = cg::this_grid();
;     const int tid0 = threadIdx.x, wave0 = __builtin_amdgcn_readfirstlane(tid0 >> 6);
	.amdhsa_kernel _Z9trunk_fwd4Args
		.amdhsa_group_segment_fixed_size 0
		.amdhsa_private_segment_fixed_size 0
		.amdhsa_kernarg_size 440
		.amdhsa_user_sgpr_count 2
		.amdhsa_user_sgpr_dispatch_ptr 0
		.amdhsa_user_sgpr_queue_ptr 0
		.amdhsa_user_sgpr_kernarg_segment_ptr 1
		.amdhsa_user_sgpr_dispatch_id 0
		.amdhsa_user_sgpr_kernarg_preload_length 0
		.amdhsa_user_sgpr_kernarg_preload_offset 0
		.amdhsa_user_sgpr_private_segment_size 0
		.amdhsa_uses_dynamic_stack 0
		.amdhsa_enable_private_segment 0
		.amdhsa_system_sgpr_workgroup_id_x 1
		.amdhsa_system_sgpr_workgroup_id_y 0
		.amdhsa_system_sgpr_workgroup_id_z 0
		.amdhsa_system_sgpr_workgroup_info 0
		.amdhsa_system_vgpr_workitem_id 2
		.amdhsa_next_free_vgpr 256
		.amdhsa_next_free_sgpr 102
		.amdhsa_accum_offset 256
		.amdhsa_reserve_vcc 1
		.amdhsa_float_round_mode_32 0
		.amdhsa_float_round_mode_16_64 0
		.amdhsa_float_denorm_mode_32 3
		.amdhsa_float_denorm_mode_16_64 3
		.amdhsa_dx10_clamp 1
		.amdhsa_ieee_mode 1
		.amdhsa_fp16_overflow 0
		.amdhsa_tg_split 0
		.amdhsa_exception_fp_ieee_invalid_op 0
		.amdhsa_exception_fp_denorm_src 0
		.amdhsa_exception_fp_ieee_div_zero 0
		.amdhsa_exception_fp_ieee_overflow 0
		.amdhsa_exception_fp_ieee_underflow 0
		.amdhsa_exception_fp_ieee_inexact 0
		.amdhsa_exception_int_div_zero 0
	.end_amdhsa_kernel

; #define LAS __attribute__((address_space(3)))
; __global__ void __launch_bounds__(512, 2) trunk_fwd(Args a_) {
;     extern __shared__ __attribute__((aligned(16))) unsigned char lds_raw[];
;     LAS unsigned char* lds = (LAS unsigned char*)lds_raw;
;     cg::grid_group grid = cg::this_grid();
;     const int tid0 = threadIdx.x, wave0 = __builtin_amdgcn_readfirstlane(tid0 >> 6);
amdhsa.kernels:
  - .agpr_count:     0
    .args:
      - .offset:         0
        .size:           184
        .value_kind:     by_value
      - .offset:         184
        .size:           4
        .value_kind:     hidden_block_count_x
      - .offset:         188
        .size:           4
        .value_kind:     hidden_block_count_y
      - .offset:         192
        .size:           4
        .value_kind:     hidden_block_count_z
      - .offset:         196
        .size:           2
        .value_kind:     hidden_group_size_x
      - .offset:         198
        .size:           2
        .value_kind:     hidden_group_size_y
      - .offset:         200
        .size:           2
        .value_kind:     hidden_group_size_z
      - .offset:         202
        .size:           2
        .value_kind:     hidden_remainder_x
      - .offset:         204
        .size:           2
        .value_kind:     hidden_remainder_y
      - .offset:         206
        .size:           2
        .value_kind:     hidden_remainder_z
      - .offset:         224
        .size:           8
        .value_kind:     hidden_global_offset_x
      - .offset:         232
        .size:           8
        .value_kind:     hidden_global_offset_y
      - .offset:         240
        .size:           8
        .value_kind:     hidden_global_offset_z
      - .offset:         248
        .size:           2
        .value_kind:     hidden_grid_dims
      - .offset:         272
        .size:           8
        .value_kind:     hidden_multigrid_sync_arg
      - .offset:         304
        .size:           4
        .value_kind:     hidden_dynamic_lds_size
    .group_segment_fixed_size: 0
    .kernarg_segment_align: 8
    .kernarg_segment_size: 440
    .language:       OpenCL C
    .language_version:
      - 2
      - 0
    .max_flat_workgroup_size: 512
    .name:           _Z9trunk_fwd4Args
    .private_segment_fixed_size: 0
    .sgpr_count:     108
    .sgpr_spill_count: 166
    .symbol:         _Z9trunk_fwd4Args.kd
    .uniform_work_group_size: 1
    .uses_dynamic_stack: false
    .vgpr_count:     256
    .vgpr_spill_count: 0
    .wavefront_size: 64
